# context filter half units also use the f32-operand matrix instructions for the last filter layer
# speedup vs baseline: 1.0293x; 1.0064x over previous
.LBB0_30:
	v_and_b32_e32 v34, 15, v170
	v_bfe_u32 v35, v170, 4, 2
	v_lshrrev_b32_e32 v36, 6, v170
	v_lshlrev_b32_e32 v37, 8, v34
	v_lshl_add_u32 v37, v35, 2, v37
	v_add_u32_e32 v37, 0x3210, v37
	ds_read_b32 v78, v37 offset:0
	ds_read_b32 v79, v37 offset:16
	ds_read_b32 v80, v37 offset:32
	ds_read_b32 v81, v37 offset:48
	ds_read_b32 v82, v37 offset:64
	ds_read_b32 v83, v37 offset:80
	ds_read_b32 v84, v37 offset:96
	ds_read_b32 v85, v37 offset:112
	ds_read_b32 v86, v37 offset:128
	ds_read_b32 v87, v37 offset:144
	ds_read_b32 v88, v37 offset:160
	ds_read_b32 v89, v37 offset:176
	ds_read_b32 v90, v37 offset:192
	ds_read_b32 v91, v37 offset:208
	ds_read_b32 v92, v37 offset:224
	ds_read_b32 v93, v37 offset:240
	ds_read_b32 v94, v37 offset:4096
	ds_read_b32 v95, v37 offset:4112
	ds_read_b32 v96, v37 offset:4128
	ds_read_b32 v97, v37 offset:4144
	ds_read_b32 v98, v37 offset:4160
	ds_read_b32 v99, v37 offset:4176
	ds_read_b32 v100, v37 offset:4192
	ds_read_b32 v101, v37 offset:4208
	ds_read_b32 v102, v37 offset:4224
	ds_read_b32 v103, v37 offset:4240
	ds_read_b32 v104, v37 offset:4256
	ds_read_b32 v105, v37 offset:4272
	ds_read_b32 v106, v37 offset:4288
	ds_read_b32 v107, v37 offset:4304
	ds_read_b32 v108, v37 offset:4320
	ds_read_b32 v109, v37 offset:4336
	v_readlane_b32 s76, v251, 42
	v_readlane_b32 s77, v251, 43
	v_readlane_b32 s80, v251, 46
	v_readlane_b32 s81, v251, 47
	v_lshl_add_u32 v38, v36, 6, v34
	s_lshl_b32 s86, s100, 9
	v_add_u32_e32 v38, s86, v38
	v_lshlrev_b32_e32 v39, 12, v35
	v_lshl_add_u32 v39, v38, 2, v39
	v_lshlrev_b32_e32 v40, 10, v38
	v_lshl_add_u32 v40, v35, 4, v40
	v_lshlrev_b32_e32 v138, 2, v38
	v_lshlrev_b32_e32 v134, 2, v35
	v_add_u32_e32 v134, s101, v134
	v_add_u32_e32 v139, 0, v134
	v_cvt_f32_u32_e32 v139, v139
	v_mul_f32_e32 v126, 0xbb800000, v139
	v_add_u32_e32 v139, 1, v134
	v_cvt_f32_u32_e32 v139, v139
	v_mul_f32_e32 v127, 0xbb800000, v139
	v_add_u32_e32 v139, 2, v134
	v_cvt_f32_u32_e32 v139, v139
	v_mul_f32_e32 v128, 0xbb800000, v139
	v_add_u32_e32 v139, 3, v134
	v_cvt_f32_u32_e32 v139, v139
	v_mul_f32_e32 v129, 0xbb800000, v139
	v_add_u32_e32 v139, 16, v134
	v_cvt_f32_u32_e32 v139, v139
	v_mul_f32_e32 v130, 0xbb800000, v139
	v_add_u32_e32 v139, 17, v134
	v_cvt_f32_u32_e32 v139, v139
	v_mul_f32_e32 v131, 0xbb800000, v139
	v_add_u32_e32 v139, 18, v134
	v_cvt_f32_u32_e32 v139, v139
	v_mul_f32_e32 v132, 0xbb800000, v139
	v_add_u32_e32 v139, 19, v134
	v_cvt_f32_u32_e32 v139, v139
	v_mul_f32_e32 v133, 0xbb800000, v139
	v_and_b32_e32 v139, 63, v170
	v_xor_b32_e32 v135, 16, v139
	v_lshlrev_b32_e32 v135, 2, v135
	v_xor_b32_e32 v136, 32, v139
	v_lshlrev_b32_e32 v136, 2, v136
	v_cmp_eq_u32_e32 vcc, 0, v35
	s_cmp_lg_u32 s100, 0
	s_cselect_b64 s[86:87], -1, 0
	s_and_b64 vcc, vcc, s[86:87]
	s_cmp_eq_u32 s101, 0
	s_cselect_b64 s[86:87], -1, 0
	s_and_b64 vcc, vcc, s[86:87]
	v_mov_b32_e32 v137, 1.0
	v_cndmask_b32_e32 v137, v137, v41, vcc
	s_waitcnt lgkmcnt(0)
	global_load_dword v140, v138, s[80:81] offset:0
	global_load_dword v141, v138, s[80:81] offset:64
	global_load_dword v142, v138, s[80:81] offset:128
	global_load_dword v143, v138, s[80:81] offset:192
	s_add_u32 s82, s76, 0x0
	s_addc_u32 s83, s77, 0
	global_load_dword v172, v39, s[82:83] offset:0
	global_load_dword v188, v39, s[82:83] offset:64
	global_load_dword v204, v39, s[82:83] offset:128
	global_load_dword v110, v39, s[82:83] offset:192
	s_add_u32 s82, s76, 0x4000
	s_addc_u32 s83, s77, 0
	global_load_dword v173, v39, s[82:83] offset:0
	global_load_dword v189, v39, s[82:83] offset:64
	global_load_dword v205, v39, s[82:83] offset:128
	global_load_dword v111, v39, s[82:83] offset:192
	s_add_u32 s82, s76, 0x8000
	s_addc_u32 s83, s77, 0
	global_load_dword v174, v39, s[82:83] offset:0
	global_load_dword v190, v39, s[82:83] offset:64
	global_load_dword v206, v39, s[82:83] offset:128
	global_load_dword v112, v39, s[82:83] offset:192
	s_add_u32 s82, s76, 0xc000
	s_addc_u32 s83, s77, 0
	global_load_dword v175, v39, s[82:83] offset:0
	global_load_dword v191, v39, s[82:83] offset:64
	global_load_dword v207, v39, s[82:83] offset:128
	global_load_dword v113, v39, s[82:83] offset:192
	s_add_u32 s82, s76, 0x10000
	s_addc_u32 s83, s77, 0
	global_load_dword v176, v39, s[82:83] offset:0
	global_load_dword v192, v39, s[82:83] offset:64
	global_load_dword v208, v39, s[82:83] offset:128
	global_load_dword v114, v39, s[82:83] offset:192
	s_add_u32 s82, s76, 0x14000
	s_addc_u32 s83, s77, 0
	global_load_dword v177, v39, s[82:83] offset:0
	global_load_dword v193, v39, s[82:83] offset:64
	global_load_dword v209, v39, s[82:83] offset:128
	global_load_dword v115, v39, s[82:83] offset:192
	s_add_u32 s82, s76, 0x18000
	s_addc_u32 s83, s77, 0
	global_load_dword v178, v39, s[82:83] offset:0
	global_load_dword v194, v39, s[82:83] offset:64
	global_load_dword v210, v39, s[82:83] offset:128
	global_load_dword v116, v39, s[82:83] offset:192
	s_add_u32 s82, s76, 0x1c000
	s_addc_u32 s83, s77, 0
	global_load_dword v179, v39, s[82:83] offset:0
	global_load_dword v195, v39, s[82:83] offset:64
	global_load_dword v211, v39, s[82:83] offset:128
	global_load_dword v117, v39, s[82:83] offset:192
	s_waitcnt vmcnt(28)
	v_mfma_f32_16x16x4_f32 v[2:5], v78, v172, 0
	v_mfma_f32_16x16x4_f32 v[6:9], v78, v188, 0
	v_mfma_f32_16x16x4_f32 v[10:13], v78, v204, 0
	v_mfma_f32_16x16x4_f32 v[14:17], v78, v110, 0
	v_mfma_f32_16x16x4_f32 v[18:21], v94, v172, 0
	v_mfma_f32_16x16x4_f32 v[22:25], v94, v188, 0
	v_mfma_f32_16x16x4_f32 v[26:29], v94, v204, 0
	v_mfma_f32_16x16x4_f32 v[30:33], v94, v110, 0
	s_add_u32 s82, s76, 0x20000
	s_addc_u32 s83, s77, 0
	global_load_dword v180, v39, s[82:83] offset:0
	global_load_dword v196, v39, s[82:83] offset:64
	global_load_dword v212, v39, s[82:83] offset:128
	global_load_dword v118, v39, s[82:83] offset:192
	s_waitcnt vmcnt(28)
	v_mfma_f32_16x16x4_f32 v[2:5], v79, v173, v[2:5]
	v_mfma_f32_16x16x4_f32 v[6:9], v79, v189, v[6:9]
	v_mfma_f32_16x16x4_f32 v[10:13], v79, v205, v[10:13]
	v_mfma_f32_16x16x4_f32 v[14:17], v79, v111, v[14:17]
	v_mfma_f32_16x16x4_f32 v[18:21], v95, v173, v[18:21]
	v_mfma_f32_16x16x4_f32 v[22:25], v95, v189, v[22:25]
	v_mfma_f32_16x16x4_f32 v[26:29], v95, v205, v[26:29]
	v_mfma_f32_16x16x4_f32 v[30:33], v95, v111, v[30:33]
	s_add_u32 s82, s76, 0x24000
	s_addc_u32 s83, s77, 0
	global_load_dword v181, v39, s[82:83] offset:0
	global_load_dword v197, v39, s[82:83] offset:64
	global_load_dword v213, v39, s[82:83] offset:128
	global_load_dword v119, v39, s[82:83] offset:192
	s_waitcnt vmcnt(28)
	v_mfma_f32_16x16x4_f32 v[2:5], v80, v174, v[2:5]
	v_mfma_f32_16x16x4_f32 v[6:9], v80, v190, v[6:9]
	v_mfma_f32_16x16x4_f32 v[10:13], v80, v206, v[10:13]
	v_mfma_f32_16x16x4_f32 v[14:17], v80, v112, v[14:17]
	v_mfma_f32_16x16x4_f32 v[18:21], v96, v174, v[18:21]
	v_mfma_f32_16x16x4_f32 v[22:25], v96, v190, v[22:25]
	v_mfma_f32_16x16x4_f32 v[26:29], v96, v206, v[26:29]
	v_mfma_f32_16x16x4_f32 v[30:33], v96, v112, v[30:33]
	s_add_u32 s82, s76, 0x28000
	s_addc_u32 s83, s77, 0
	global_load_dword v182, v39, s[82:83] offset:0
	global_load_dword v198, v39, s[82:83] offset:64
	global_load_dword v214, v39, s[82:83] offset:128
	global_load_dword v120, v39, s[82:83] offset:192
	s_waitcnt vmcnt(28)
	v_mfma_f32_16x16x4_f32 v[2:5], v81, v175, v[2:5]
	v_mfma_f32_16x16x4_f32 v[6:9], v81, v191, v[6:9]
	v_mfma_f32_16x16x4_f32 v[10:13], v81, v207, v[10:13]
	v_mfma_f32_16x16x4_f32 v[14:17], v81, v113, v[14:17]
	v_mfma_f32_16x16x4_f32 v[18:21], v97, v175, v[18:21]
	v_mfma_f32_16x16x4_f32 v[22:25], v97, v191, v[22:25]
	v_mfma_f32_16x16x4_f32 v[26:29], v97, v207, v[26:29]
	v_mfma_f32_16x16x4_f32 v[30:33], v97, v113, v[30:33]
	s_add_u32 s82, s76, 0x2c000
	s_addc_u32 s83, s77, 0
	global_load_dword v183, v39, s[82:83] offset:0
	global_load_dword v199, v39, s[82:83] offset:64
	global_load_dword v215, v39, s[82:83] offset:128
	global_load_dword v121, v39, s[82:83] offset:192
	s_waitcnt vmcnt(28)
	v_mfma_f32_16x16x4_f32 v[2:5], v82, v176, v[2:5]
	v_mfma_f32_16x16x4_f32 v[6:9], v82, v192, v[6:9]
	v_mfma_f32_16x16x4_f32 v[10:13], v82, v208, v[10:13]
	v_mfma_f32_16x16x4_f32 v[14:17], v82, v114, v[14:17]
	v_mfma_f32_16x16x4_f32 v[18:21], v98, v176, v[18:21]
	v_mfma_f32_16x16x4_f32 v[22:25], v98, v192, v[22:25]
	v_mfma_f32_16x16x4_f32 v[26:29], v98, v208, v[26:29]
	v_mfma_f32_16x16x4_f32 v[30:33], v98, v114, v[30:33]
	s_add_u32 s82, s76, 0x30000
	s_addc_u32 s83, s77, 0
	global_load_dword v184, v39, s[82:83] offset:0
	global_load_dword v200, v39, s[82:83] offset:64
	global_load_dword v216, v39, s[82:83] offset:128
	global_load_dword v122, v39, s[82:83] offset:192
	s_waitcnt vmcnt(28)
	v_mfma_f32_16x16x4_f32 v[2:5], v83, v177, v[2:5]
	v_mfma_f32_16x16x4_f32 v[6:9], v83, v193, v[6:9]
	v_mfma_f32_16x16x4_f32 v[10:13], v83, v209, v[10:13]
	v_mfma_f32_16x16x4_f32 v[14:17], v83, v115, v[14:17]
	v_mfma_f32_16x16x4_f32 v[18:21], v99, v177, v[18:21]
	v_mfma_f32_16x16x4_f32 v[22:25], v99, v193, v[22:25]
	v_mfma_f32_16x16x4_f32 v[26:29], v99, v209, v[26:29]
	v_mfma_f32_16x16x4_f32 v[30:33], v99, v115, v[30:33]
	s_add_u32 s82, s76, 0x34000
	s_addc_u32 s83, s77, 0
	global_load_dword v185, v39, s[82:83] offset:0
	global_load_dword v201, v39, s[82:83] offset:64
	global_load_dword v217, v39, s[82:83] offset:128
	global_load_dword v123, v39, s[82:83] offset:192
	s_waitcnt vmcnt(28)
	v_mfma_f32_16x16x4_f32 v[2:5], v84, v178, v[2:5]
	v_mfma_f32_16x16x4_f32 v[6:9], v84, v194, v[6:9]
	v_mfma_f32_16x16x4_f32 v[10:13], v84, v210, v[10:13]
	v_mfma_f32_16x16x4_f32 v[14:17], v84, v116, v[14:17]
	v_mfma_f32_16x16x4_f32 v[18:21], v100, v178, v[18:21]
	v_mfma_f32_16x16x4_f32 v[22:25], v100, v194, v[22:25]
	v_mfma_f32_16x16x4_f32 v[26:29], v100, v210, v[26:29]
	v_mfma_f32_16x16x4_f32 v[30:33], v100, v116, v[30:33]
	s_add_u32 s82, s76, 0x38000
	s_addc_u32 s83, s77, 0
	global_load_dword v186, v39, s[82:83] offset:0
	global_load_dword v202, v39, s[82:83] offset:64
	global_load_dword v218, v39, s[82:83] offset:128
	global_load_dword v124, v39, s[82:83] offset:192
	s_waitcnt vmcnt(28)
	v_mfma_f32_16x16x4_f32 v[2:5], v85, v179, v[2:5]
	v_mfma_f32_16x16x4_f32 v[6:9], v85, v195, v[6:9]
	v_mfma_f32_16x16x4_f32 v[10:13], v85, v211, v[10:13]
	v_mfma_f32_16x16x4_f32 v[14:17], v85, v117, v[14:17]
	v_mfma_f32_16x16x4_f32 v[18:21], v101, v179, v[18:21]
	v_mfma_f32_16x16x4_f32 v[22:25], v101, v195, v[22:25]
	v_mfma_f32_16x16x4_f32 v[26:29], v101, v211, v[26:29]
	v_mfma_f32_16x16x4_f32 v[30:33], v101, v117, v[30:33]
	s_add_u32 s82, s76, 0x3c000
	s_addc_u32 s83, s77, 0
	global_load_dword v187, v39, s[82:83] offset:0
	global_load_dword v203, v39, s[82:83] offset:64
	global_load_dword v219, v39, s[82:83] offset:128
	global_load_dword v125, v39, s[82:83] offset:192
	s_waitcnt vmcnt(28)
	v_mfma_f32_16x16x4_f32 v[2:5], v86, v180, v[2:5]
	v_mfma_f32_16x16x4_f32 v[6:9], v86, v196, v[6:9]
	v_mfma_f32_16x16x4_f32 v[10:13], v86, v212, v[10:13]
	v_mfma_f32_16x16x4_f32 v[14:17], v86, v118, v[14:17]
	v_mfma_f32_16x16x4_f32 v[18:21], v102, v180, v[18:21]
	v_mfma_f32_16x16x4_f32 v[22:25], v102, v196, v[22:25]
	v_mfma_f32_16x16x4_f32 v[26:29], v102, v212, v[26:29]
	v_mfma_f32_16x16x4_f32 v[30:33], v102, v118, v[30:33]
	s_waitcnt vmcnt(24)
	v_mfma_f32_16x16x4_f32 v[2:5], v87, v181, v[2:5]
	v_mfma_f32_16x16x4_f32 v[6:9], v87, v197, v[6:9]
	v_mfma_f32_16x16x4_f32 v[10:13], v87, v213, v[10:13]
	v_mfma_f32_16x16x4_f32 v[14:17], v87, v119, v[14:17]
	v_mfma_f32_16x16x4_f32 v[18:21], v103, v181, v[18:21]
	v_mfma_f32_16x16x4_f32 v[22:25], v103, v197, v[22:25]
	v_mfma_f32_16x16x4_f32 v[26:29], v103, v213, v[26:29]
	v_mfma_f32_16x16x4_f32 v[30:33], v103, v119, v[30:33]
	s_waitcnt vmcnt(20)
	v_mfma_f32_16x16x4_f32 v[2:5], v88, v182, v[2:5]
	v_mfma_f32_16x16x4_f32 v[6:9], v88, v198, v[6:9]
	v_mfma_f32_16x16x4_f32 v[10:13], v88, v214, v[10:13]
	v_mfma_f32_16x16x4_f32 v[14:17], v88, v120, v[14:17]
	v_mfma_f32_16x16x4_f32 v[18:21], v104, v182, v[18:21]
	v_mfma_f32_16x16x4_f32 v[22:25], v104, v198, v[22:25]
	v_mfma_f32_16x16x4_f32 v[26:29], v104, v214, v[26:29]
	v_mfma_f32_16x16x4_f32 v[30:33], v104, v120, v[30:33]
	s_waitcnt vmcnt(16)
	v_mfma_f32_16x16x4_f32 v[2:5], v89, v183, v[2:5]
	v_mfma_f32_16x16x4_f32 v[6:9], v89, v199, v[6:9]
	v_mfma_f32_16x16x4_f32 v[10:13], v89, v215, v[10:13]
	v_mfma_f32_16x16x4_f32 v[14:17], v89, v121, v[14:17]
	v_mfma_f32_16x16x4_f32 v[18:21], v105, v183, v[18:21]
	v_mfma_f32_16x16x4_f32 v[22:25], v105, v199, v[22:25]
	v_mfma_f32_16x16x4_f32 v[26:29], v105, v215, v[26:29]
	v_mfma_f32_16x16x4_f32 v[30:33], v105, v121, v[30:33]
	s_waitcnt vmcnt(12)
	v_mfma_f32_16x16x4_f32 v[2:5], v90, v184, v[2:5]
	v_mfma_f32_16x16x4_f32 v[6:9], v90, v200, v[6:9]
	v_mfma_f32_16x16x4_f32 v[10:13], v90, v216, v[10:13]
	v_mfma_f32_16x16x4_f32 v[14:17], v90, v122, v[14:17]
	v_mfma_f32_16x16x4_f32 v[18:21], v106, v184, v[18:21]
	v_mfma_f32_16x16x4_f32 v[22:25], v106, v200, v[22:25]
	v_mfma_f32_16x16x4_f32 v[26:29], v106, v216, v[26:29]
	v_mfma_f32_16x16x4_f32 v[30:33], v106, v122, v[30:33]
	s_waitcnt vmcnt(8)
	v_mfma_f32_16x16x4_f32 v[2:5], v91, v185, v[2:5]
	v_mfma_f32_16x16x4_f32 v[6:9], v91, v201, v[6:9]
	v_mfma_f32_16x16x4_f32 v[10:13], v91, v217, v[10:13]
	v_mfma_f32_16x16x4_f32 v[14:17], v91, v123, v[14:17]
	v_mfma_f32_16x16x4_f32 v[18:21], v107, v185, v[18:21]
	v_mfma_f32_16x16x4_f32 v[22:25], v107, v201, v[22:25]
	v_mfma_f32_16x16x4_f32 v[26:29], v107, v217, v[26:29]
	v_mfma_f32_16x16x4_f32 v[30:33], v107, v123, v[30:33]
	s_waitcnt vmcnt(4)
	v_mfma_f32_16x16x4_f32 v[2:5], v92, v186, v[2:5]
	v_mfma_f32_16x16x4_f32 v[6:9], v92, v202, v[6:9]
	v_mfma_f32_16x16x4_f32 v[10:13], v92, v218, v[10:13]
	v_mfma_f32_16x16x4_f32 v[14:17], v92, v124, v[14:17]
	v_mfma_f32_16x16x4_f32 v[18:21], v108, v186, v[18:21]
	v_mfma_f32_16x16x4_f32 v[22:25], v108, v202, v[22:25]
	v_mfma_f32_16x16x4_f32 v[26:29], v108, v218, v[26:29]
	v_mfma_f32_16x16x4_f32 v[30:33], v108, v124, v[30:33]
	s_waitcnt vmcnt(0)
	v_mfma_f32_16x16x4_f32 v[2:5], v93, v187, v[2:5]
	v_mfma_f32_16x16x4_f32 v[6:9], v93, v203, v[6:9]
	v_mfma_f32_16x16x4_f32 v[10:13], v93, v219, v[10:13]
	v_mfma_f32_16x16x4_f32 v[14:17], v93, v125, v[14:17]
	v_mfma_f32_16x16x4_f32 v[18:21], v109, v187, v[18:21]
	v_mfma_f32_16x16x4_f32 v[22:25], v109, v203, v[22:25]
	v_mfma_f32_16x16x4_f32 v[26:29], v109, v219, v[26:29]
	v_mfma_f32_16x16x4_f32 v[30:33], v109, v125, v[30:33]
	s_nop 7
	s_nop 7
	s_nop 3
	v_mul_f32_e64 v148, |v140|, v126
	v_mul_f32_e64 v149, |v140|, v127
	v_mul_f32_e64 v150, |v140|, v128
	v_mul_f32_e64 v151, |v140|, v129
	v_mul_f32_e64 v152, |v140|, v130
	v_mul_f32_e64 v153, |v140|, v131
	v_mul_f32_e64 v154, |v140|, v132
	v_mul_f32_e64 v155, |v140|, v133
	v_mul_f32_e32 v148, 0x3fb8aa3b, v148
	v_mul_f32_e32 v149, 0x3fb8aa3b, v149
	v_mul_f32_e32 v150, 0x3fb8aa3b, v150
	v_mul_f32_e32 v151, 0x3fb8aa3b, v151
	v_mul_f32_e32 v152, 0x3fb8aa3b, v152
	v_mul_f32_e32 v153, 0x3fb8aa3b, v153
	v_mul_f32_e32 v154, 0x3fb8aa3b, v154
	v_mul_f32_e32 v155, 0x3fb8aa3b, v155
	v_exp_f32_e32 v148, v148
	v_exp_f32_e32 v149, v149
	v_exp_f32_e32 v150, v150
	v_exp_f32_e32 v151, v151
	v_exp_f32_e32 v152, v152
	v_exp_f32_e32 v153, v153
	v_exp_f32_e32 v154, v154
	v_exp_f32_e32 v155, v155
	v_mul_f32_e32 v2, v148, v2
	v_mul_f32_e32 v3, v149, v3
	v_mul_f32_e32 v4, v150, v4
	v_mul_f32_e32 v5, v151, v5
	v_mul_f32_e32 v18, v152, v18
	v_mul_f32_e32 v19, v153, v19
	v_mul_f32_e32 v20, v154, v20
	v_mul_f32_e32 v21, v155, v21
	v_mul_f32_e32 v144, v2, v2
	v_mul_f32_e32 v144, v137, v144
	v_fmac_f32_e32 v144, v3, v3
	v_fmac_f32_e32 v144, v4, v4
	v_fmac_f32_e32 v144, v5, v5
	v_fmac_f32_e32 v144, v18, v18
	v_fmac_f32_e32 v144, v19, v19
	v_fmac_f32_e32 v144, v20, v20
	v_fmac_f32_e32 v144, v21, v21
	s_add_u32 s84, s40, 0x0
	s_addc_u32 s85, s41, 0
	global_store_dwordx4 v40, v[2:5], s[84:85]
	global_store_dwordx4 v40, v[18:21], s[84:85] offset:64
	v_mul_f32_e64 v148, |v141|, v126
	v_mul_f32_e64 v149, |v141|, v127
	v_mul_f32_e64 v150, |v141|, v128
	v_mul_f32_e64 v151, |v141|, v129
	v_mul_f32_e64 v152, |v141|, v130
	v_mul_f32_e64 v153, |v141|, v131
	v_mul_f32_e64 v154, |v141|, v132
	v_mul_f32_e64 v155, |v141|, v133
	v_mul_f32_e32 v148, 0x3fb8aa3b, v148
	v_mul_f32_e32 v149, 0x3fb8aa3b, v149
	v_mul_f32_e32 v150, 0x3fb8aa3b, v150
	v_mul_f32_e32 v151, 0x3fb8aa3b, v151
	v_mul_f32_e32 v152, 0x3fb8aa3b, v152
	v_mul_f32_e32 v153, 0x3fb8aa3b, v153
	v_mul_f32_e32 v154, 0x3fb8aa3b, v154
	v_mul_f32_e32 v155, 0x3fb8aa3b, v155
	v_exp_f32_e32 v148, v148
	v_exp_f32_e32 v149, v149
	v_exp_f32_e32 v150, v150
	v_exp_f32_e32 v151, v151
	v_exp_f32_e32 v152, v152
	v_exp_f32_e32 v153, v153
	v_exp_f32_e32 v154, v154
	v_exp_f32_e32 v155, v155
	v_mul_f32_e32 v6, v148, v6
	v_mul_f32_e32 v7, v149, v7
	v_mul_f32_e32 v8, v150, v8
	v_mul_f32_e32 v9, v151, v9
	v_mul_f32_e32 v22, v152, v22
	v_mul_f32_e32 v23, v153, v23
	v_mul_f32_e32 v24, v154, v24
	v_mul_f32_e32 v25, v155, v25
	v_mul_f32_e32 v145, v6, v6
	v_mul_f32_e32 v145, v137, v145
	v_fmac_f32_e32 v145, v7, v7
	v_fmac_f32_e32 v145, v8, v8
	v_fmac_f32_e32 v145, v9, v9
	v_fmac_f32_e32 v145, v22, v22
	v_fmac_f32_e32 v145, v23, v23
	v_fmac_f32_e32 v145, v24, v24
	v_fmac_f32_e32 v145, v25, v25
	s_add_u32 s84, s40, 0x4000
	s_addc_u32 s85, s41, 0
	global_store_dwordx4 v40, v[6:9], s[84:85]
	global_store_dwordx4 v40, v[22:25], s[84:85] offset:64
	v_mul_f32_e64 v148, |v142|, v126
	v_mul_f32_e64 v149, |v142|, v127
	v_mul_f32_e64 v150, |v142|, v128
	v_mul_f32_e64 v151, |v142|, v129
	v_mul_f32_e64 v152, |v142|, v130
	v_mul_f32_e64 v153, |v142|, v131
	v_mul_f32_e64 v154, |v142|, v132
	v_mul_f32_e64 v155, |v142|, v133
	v_mul_f32_e32 v148, 0x3fb8aa3b, v148
	v_mul_f32_e32 v149, 0x3fb8aa3b, v149
	v_mul_f32_e32 v150, 0x3fb8aa3b, v150
	v_mul_f32_e32 v151, 0x3fb8aa3b, v151
	v_mul_f32_e32 v152, 0x3fb8aa3b, v152
	v_mul_f32_e32 v153, 0x3fb8aa3b, v153
	v_mul_f32_e32 v154, 0x3fb8aa3b, v154
	v_mul_f32_e32 v155, 0x3fb8aa3b, v155
	v_exp_f32_e32 v148, v148
	v_exp_f32_e32 v149, v149
	v_exp_f32_e32 v150, v150
	v_exp_f32_e32 v151, v151
	v_exp_f32_e32 v152, v152
	v_exp_f32_e32 v153, v153
	v_exp_f32_e32 v154, v154
	v_exp_f32_e32 v155, v155
	v_mul_f32_e32 v10, v148, v10
	v_mul_f32_e32 v11, v149, v11
	v_mul_f32_e32 v12, v150, v12
	v_mul_f32_e32 v13, v151, v13
	v_mul_f32_e32 v26, v152, v26
	v_mul_f32_e32 v27, v153, v27
	v_mul_f32_e32 v28, v154, v28
	v_mul_f32_e32 v29, v155, v29
	v_mul_f32_e32 v146, v10, v10
	v_mul_f32_e32 v146, v137, v146
	v_fmac_f32_e32 v146, v11, v11
	v_fmac_f32_e32 v146, v12, v12
	v_fmac_f32_e32 v146, v13, v13
	v_fmac_f32_e32 v146, v26, v26
	v_fmac_f32_e32 v146, v27, v27
	v_fmac_f32_e32 v146, v28, v28
	v_fmac_f32_e32 v146, v29, v29
	s_add_u32 s84, s40, 0x8000
	s_addc_u32 s85, s41, 0
	global_store_dwordx4 v40, v[10:13], s[84:85]
	global_store_dwordx4 v40, v[26:29], s[84:85] offset:64
	v_mul_f32_e64 v148, |v143|, v126
	v_mul_f32_e64 v149, |v143|, v127
	v_mul_f32_e64 v150, |v143|, v128
	v_mul_f32_e64 v151, |v143|, v129
	v_mul_f32_e64 v152, |v143|, v130
	v_mul_f32_e64 v153, |v143|, v131
	v_mul_f32_e64 v154, |v143|, v132
	v_mul_f32_e64 v155, |v143|, v133
	v_mul_f32_e32 v148, 0x3fb8aa3b, v148
	v_mul_f32_e32 v149, 0x3fb8aa3b, v149
	v_mul_f32_e32 v150, 0x3fb8aa3b, v150
	v_mul_f32_e32 v151, 0x3fb8aa3b, v151
	v_mul_f32_e32 v152, 0x3fb8aa3b, v152
	v_mul_f32_e32 v153, 0x3fb8aa3b, v153
	v_mul_f32_e32 v154, 0x3fb8aa3b, v154
	v_mul_f32_e32 v155, 0x3fb8aa3b, v155
	v_exp_f32_e32 v148, v148
	v_exp_f32_e32 v149, v149
	v_exp_f32_e32 v150, v150
	v_exp_f32_e32 v151, v151
	v_exp_f32_e32 v152, v152
	v_exp_f32_e32 v153, v153
	v_exp_f32_e32 v154, v154
	v_exp_f32_e32 v155, v155
	v_mul_f32_e32 v14, v148, v14
	v_mul_f32_e32 v15, v149, v15
	v_mul_f32_e32 v16, v150, v16
	v_mul_f32_e32 v17, v151, v17
	v_mul_f32_e32 v30, v152, v30
	v_mul_f32_e32 v31, v153, v31
	v_mul_f32_e32 v32, v154, v32
	v_mul_f32_e32 v33, v155, v33
	v_mul_f32_e32 v147, v14, v14
	v_mul_f32_e32 v147, v137, v147
	v_fmac_f32_e32 v147, v15, v15
	v_fmac_f32_e32 v147, v16, v16
	v_fmac_f32_e32 v147, v17, v17
	v_fmac_f32_e32 v147, v30, v30
	v_fmac_f32_e32 v147, v31, v31
	v_fmac_f32_e32 v147, v32, v32
	v_fmac_f32_e32 v147, v33, v33
	s_add_u32 s84, s40, 0xc000
	s_addc_u32 s85, s41, 0
	global_store_dwordx4 v40, v[14:17], s[84:85]
	global_store_dwordx4 v40, v[30:33], s[84:85] offset:64
	ds_bpermute_b32 v148, v135, v144
	ds_bpermute_b32 v149, v135, v145
	ds_bpermute_b32 v150, v135, v146
	ds_bpermute_b32 v151, v135, v147
	s_waitcnt lgkmcnt(0)
	v_add_f32_e32 v144, v144, v148
	v_add_f32_e32 v145, v145, v149
	v_add_f32_e32 v146, v146, v150
	v_add_f32_e32 v147, v147, v151
	ds_bpermute_b32 v148, v136, v144
	ds_bpermute_b32 v149, v136, v145
	ds_bpermute_b32 v150, v136, v146
	ds_bpermute_b32 v151, v136, v147
	s_waitcnt lgkmcnt(0)
	v_add_f32_e32 v144, v144, v148
	v_add_f32_e32 v145, v145, v149
	v_add_f32_e32 v146, v146, v150
	v_add_f32_e32 v147, v147, v151
	global_store_dword v138, v144, s[26:27] offset:0
	global_store_dword v138, v145, s[26:27] offset:64
	global_store_dword v138, v146, s[26:27] offset:128
	global_store_dword v138, v147, s[26:27] offset:192
	s_nop 1
	s_mov_b64 s[26:27], 0
